# P52 added on P62 stack: remaining DPP row-sum chains finish the xor-16 step with v_permlane16_swap (attention epilogues, combine, row passes)
# baseline (speedup 1.0000x reference)
.LBB0_249:
	s_min_i32 s7, s6, 0x8000
	s_ashr_i32 s7, s7, 11
	s_mul_hi_i32 s9, s7, 0x6000
	s_mulk_i32 s7, 0x6000
	s_add_u32 s7, s44, s7
	s_addc_u32 s9, s45, s9
	s_add_u32 s12, s7, 0x1000
	s_addc_u32 s13, s9, 0
	v_lshl_add_u64 v[66:67], v[116:117], 2, s[12:13]
	global_load_dwordx4 v[128:131], v[66:67], off
	v_lshl_add_u64 v[212:213], v[118:119], 2, s[12:13]
	global_load_dwordx4 v[200:203], v[212:213], off
	v_lshl_add_u64 v[212:213], v[120:121], 2, s[12:13]
	global_load_dwordx4 v[204:207], v[212:213], off
	v_lshl_add_u64 v[212:213], v[122:123], 2, s[12:13]
	global_load_dwordx4 v[208:211], v[212:213], off
	s_ashr_i32 s7, s6, 31
	s_lshl_b64 s[14:15], s[6:7], 11
	v_lshl_add_u64 v[132:133], v[126:127], 0, s[14:15]
	s_waitcnt vmcnt(7)
	v_mul_f32_e32 v64, v17, v17
	s_waitcnt vmcnt(6)
	v_mul_f32_e32 v134, v23, v23
	s_waitcnt vmcnt(5)
	v_mul_f32_e32 v135, v25, v25
	v_mul_f32_e32 v136, v27, v27
	v_fmac_f32_e32 v64, v16, v16
	v_fmac_f32_e32 v134, v22, v22
	s_waitcnt vmcnt(4)
	v_mul_f32_e32 v137, v29, v29
	v_mul_f32_e32 v138, v31, v31
	v_fmac_f32_e32 v135, v24, v24
	v_fmac_f32_e32 v136, v26, v26
	v_fmac_f32_e32 v137, v28, v28
	v_fmac_f32_e32 v138, v30, v30
	s_waitcnt vmcnt(0)
	v_pk_add_f32 v[128:129], v[128:129], 1.0 op_sel_hi:[1,0]
	v_pk_add_f32 v[130:131], v[130:131], 1.0 op_sel_hi:[1,0]
	v_pk_mul_f32 v[128:129], v[0:1], v[128:129]
	v_pk_mul_f32 v[130:131], v[2:3], v[130:131]
	v_pk_mul_f32 v[128:129], v[16:17], v[128:129]
	v_pk_mul_f32 v[130:131], v[18:19], v[130:131]
	v_cvt_pk_bf16_f32 v128, v128, v129
	s_nop 0
	v_cvt_pk_bf16_f32 v129, v130, v131
	global_store_dwordx2 v[132:133], v[128:129], off
	v_pk_add_f32 v[200:201], v[200:201], 1.0 op_sel_hi:[1,0]
	v_pk_add_f32 v[202:203], v[202:203], 1.0 op_sel_hi:[1,0]
	v_pk_mul_f32 v[200:201], v[4:5], v[200:201]
	v_pk_mul_f32 v[202:203], v[6:7], v[202:203]
	v_pk_mul_f32 v[200:201], v[20:21], v[200:201]
	v_pk_mul_f32 v[202:203], v[22:23], v[202:203]
	v_cvt_pk_bf16_f32 v200, v200, v201
	s_nop 0
	v_cvt_pk_bf16_f32 v201, v202, v203
	global_store_dwordx2 v[132:133], v[200:201], off offset:512
	v_pk_add_f32 v[204:205], v[204:205], 1.0 op_sel_hi:[1,0]
	v_pk_add_f32 v[206:207], v[206:207], 1.0 op_sel_hi:[1,0]
	v_pk_mul_f32 v[204:205], v[8:9], v[204:205]
	v_pk_mul_f32 v[206:207], v[10:11], v[206:207]
	v_pk_mul_f32 v[204:205], v[24:25], v[204:205]
	v_pk_mul_f32 v[206:207], v[26:27], v[206:207]
	v_cvt_pk_bf16_f32 v204, v204, v205
	s_nop 0
	v_cvt_pk_bf16_f32 v205, v206, v207
	global_store_dwordx2 v[132:133], v[204:205], off offset:1024
	v_mul_f32_e32 v66, v19, v19
	v_mul_f32_e32 v67, v21, v21
	v_fmac_f32_e32 v66, v18, v18
	v_fmac_f32_e32 v67, v20, v20
	v_add_f32_e32 v64, v64, v66
	v_add_f32_e32 v66, v67, v134
	v_add_f32_e32 v67, v135, v136
	v_add_f32_e32 v64, v64, v66
	v_add_f32_e32 v134, v137, v138
	v_add_f32_e32 v64, v64, v67
	v_add_f32_e32 v64, v64, v134
	s_nop 1
	v_add_f32_dpp v64, v64, v64 quad_perm:[1,0,3,2] row_mask:0xf bank_mask:0xf
	s_nop 1
	v_add_f32_dpp v64, v64, v64 quad_perm:[2,3,0,1] row_mask:0xf bank_mask:0xf
	s_nop 1
	v_add_f32_dpp v64, v64, v64 row_half_mirror row_mask:0xf bank_mask:0xf
	s_nop 1
	v_add_f32_dpp v64, v64, v64 row_mirror row_mask:0xf bank_mask:0xf
	v_mov_b32_e32 v66, v64
	s_nop 1
	v_permlane16_swap_b32_e32 v64, v66
	v_add_f32_e32 v64, v64, v66
	v_mov_b32_e32 v66, v64
	s_nop 1
	v_permlane32_swap_b32_e32 v64, v66
	v_pk_add_f32 v[208:209], v[208:209], 1.0 op_sel_hi:[1,0]
	v_pk_add_f32 v[210:211], v[210:211], 1.0 op_sel_hi:[1,0]
	v_pk_mul_f32 v[208:209], v[12:13], v[208:209]
	v_pk_mul_f32 v[210:211], v[14:15], v[210:211]
	v_pk_mul_f32 v[208:209], v[28:29], v[208:209]
	v_pk_mul_f32 v[210:211], v[30:31], v[210:211]
	v_cvt_pk_bf16_f32 v208, v208, v209
	s_nop 0
	v_cvt_pk_bf16_f32 v209, v210, v211
	global_store_dwordx2 v[132:133], v[208:209], off offset:1536
	s_and_saveexec_b64 s[12:13], s[2:3]
	s_cbranch_execz .LBB0_255
	v_add_f32_e32 v64, v64, v66
	s_lshl_b64 s[14:15], s[6:7], 6
	v_cndmask_b32_e64 v64, 0, v64, s[4:5]
	v_lshl_add_u64 v[128:129], v[124:125], 0, s[14:15]
	v_mov_b32_e32 v66, v65
	v_mov_b32_e32 v67, v65
	global_store_dwordx4 v[128:129], v[64:67], off
	s_or_b64 exec, exec, s[12:13]
	s_add_i32 s12, s26, s6
	s_cmp_gt_i32 s12, 0x8fff
	s_cbranch_scc0 .LBB0_256

.LBB0_252:
	s_min_i32 s7, s12, 0x8000
	s_ashr_i32 s7, s7, 11
	s_mul_hi_i32 s9, s7, 0x6000
	s_mulk_i32 s7, 0x6000
	s_add_u32 s7, s44, s7
	s_addc_u32 s9, s45, s9
	s_add_u32 s14, s7, 0x1000
	s_addc_u32 s15, s9, 0
	v_lshl_add_u64 v[66:67], v[116:117], 2, s[14:15]
	global_load_dwordx4 v[128:131], v[66:67], off
	v_lshl_add_u64 v[212:213], v[118:119], 2, s[14:15]
	global_load_dwordx4 v[200:203], v[212:213], off
	v_lshl_add_u64 v[212:213], v[120:121], 2, s[14:15]
	global_load_dwordx4 v[204:207], v[212:213], off
	v_lshl_add_u64 v[212:213], v[122:123], 2, s[14:15]
	global_load_dwordx4 v[208:211], v[212:213], off
	s_ashr_i32 s13, s12, 31
	s_lshl_b64 s[20:21], s[12:13], 11
	v_lshl_add_u64 v[132:133], v[126:127], 0, s[20:21]
	v_mul_f32_e32 v64, v49, v49
	v_mul_f32_e32 v134, v55, v55
	v_mul_f32_e32 v135, v57, v57
	v_mul_f32_e32 v136, v59, v59
	v_fmac_f32_e32 v64, v48, v48
	v_fmac_f32_e32 v134, v54, v54
	v_mul_f32_e32 v137, v61, v61
	v_mul_f32_e32 v138, v63, v63
	v_fmac_f32_e32 v135, v56, v56
	v_fmac_f32_e32 v136, v58, v58
	v_fmac_f32_e32 v137, v60, v60
	v_fmac_f32_e32 v138, v62, v62
	s_waitcnt vmcnt(0)
	v_pk_add_f32 v[128:129], v[128:129], 1.0 op_sel_hi:[1,0]
	v_pk_add_f32 v[130:131], v[130:131], 1.0 op_sel_hi:[1,0]
	v_pk_mul_f32 v[128:129], v[0:1], v[128:129]
	v_pk_mul_f32 v[130:131], v[2:3], v[130:131]
	v_pk_mul_f32 v[128:129], v[48:49], v[128:129]
	v_pk_mul_f32 v[130:131], v[50:51], v[130:131]
	v_cvt_pk_bf16_f32 v128, v128, v129
	s_nop 0
	v_cvt_pk_bf16_f32 v129, v130, v131
	global_store_dwordx2 v[132:133], v[128:129], off
	v_pk_add_f32 v[200:201], v[200:201], 1.0 op_sel_hi:[1,0]
	v_pk_add_f32 v[202:203], v[202:203], 1.0 op_sel_hi:[1,0]
	v_pk_mul_f32 v[200:201], v[4:5], v[200:201]
	v_pk_mul_f32 v[202:203], v[6:7], v[202:203]
	v_pk_mul_f32 v[200:201], v[52:53], v[200:201]
	v_pk_mul_f32 v[202:203], v[54:55], v[202:203]
	v_cvt_pk_bf16_f32 v200, v200, v201
	s_nop 0
	v_cvt_pk_bf16_f32 v201, v202, v203
	global_store_dwordx2 v[132:133], v[200:201], off offset:512
	v_pk_add_f32 v[204:205], v[204:205], 1.0 op_sel_hi:[1,0]
	v_pk_add_f32 v[206:207], v[206:207], 1.0 op_sel_hi:[1,0]
	v_pk_mul_f32 v[204:205], v[8:9], v[204:205]
	v_pk_mul_f32 v[206:207], v[10:11], v[206:207]
	v_pk_mul_f32 v[204:205], v[56:57], v[204:205]
	v_pk_mul_f32 v[206:207], v[58:59], v[206:207]
	v_cvt_pk_bf16_f32 v204, v204, v205
	s_nop 0
	v_cvt_pk_bf16_f32 v205, v206, v207
	global_store_dwordx2 v[132:133], v[204:205], off offset:1024
	v_mul_f32_e32 v66, v51, v51
	v_mul_f32_e32 v67, v53, v53
	v_fmac_f32_e32 v66, v50, v50
	v_fmac_f32_e32 v67, v52, v52
	v_add_f32_e32 v64, v64, v66
	v_add_f32_e32 v66, v67, v134
	v_add_f32_e32 v67, v135, v136
	v_add_f32_e32 v64, v64, v66
	v_add_f32_e32 v134, v137, v138
	v_add_f32_e32 v64, v64, v67
	v_add_f32_e32 v64, v64, v134
	s_nop 1
	v_add_f32_dpp v64, v64, v64 quad_perm:[1,0,3,2] row_mask:0xf bank_mask:0xf
	s_nop 1
	v_add_f32_dpp v64, v64, v64 quad_perm:[2,3,0,1] row_mask:0xf bank_mask:0xf
	s_nop 1
	v_add_f32_dpp v64, v64, v64 row_half_mirror row_mask:0xf bank_mask:0xf
	s_nop 1
	v_add_f32_dpp v64, v64, v64 row_mirror row_mask:0xf bank_mask:0xf
	v_mov_b32_e32 v66, v64
	s_nop 1
	v_permlane16_swap_b32_e32 v64, v66
	v_add_f32_e32 v64, v64, v66
	v_mov_b32_e32 v66, v64
	s_nop 1
	v_permlane32_swap_b32_e32 v64, v66
	v_pk_add_f32 v[208:209], v[208:209], 1.0 op_sel_hi:[1,0]
	v_pk_add_f32 v[210:211], v[210:211], 1.0 op_sel_hi:[1,0]
	v_pk_mul_f32 v[208:209], v[12:13], v[208:209]
	v_pk_mul_f32 v[210:211], v[14:15], v[210:211]
	v_pk_mul_f32 v[208:209], v[60:61], v[208:209]
	v_pk_mul_f32 v[210:211], v[62:63], v[210:211]
	v_cvt_pk_bf16_f32 v208, v208, v209
	s_nop 0
	v_cvt_pk_bf16_f32 v209, v210, v211
	global_store_dwordx2 v[132:133], v[208:209], off offset:1536
	s_and_saveexec_b64 s[14:15], s[2:3]
	s_cbranch_execz .LBB0_254
	v_add_f32_e32 v64, v64, v66
	s_lshl_b64 s[12:13], s[12:13], 6
	v_cndmask_b32_e64 v64, 0, v64, s[4:5]
	v_lshl_add_u64 v[128:129], v[124:125], 0, s[12:13]
	v_mov_b32_e32 v66, v65
	v_mov_b32_e32 v67, v65
	global_store_dwordx4 v[128:129], v[64:67], off

.LBB0_256:
	s_min_i32 s7, s12, 0x8000
	s_ashr_i32 s7, s7, 11
	s_mul_hi_i32 s9, s7, 0x6000
	s_mulk_i32 s7, 0x6000
	s_add_u32 s7, s44, s7
	s_addc_u32 s9, s45, s9
	s_add_u32 s14, s7, 0x1000
	s_addc_u32 s15, s9, 0
	v_lshl_add_u64 v[66:67], v[116:117], 2, s[14:15]
	global_load_dwordx4 v[128:131], v[66:67], off
	v_lshl_add_u64 v[212:213], v[118:119], 2, s[14:15]
	global_load_dwordx4 v[200:203], v[212:213], off
	v_lshl_add_u64 v[212:213], v[120:121], 2, s[14:15]
	global_load_dwordx4 v[204:207], v[212:213], off
	v_lshl_add_u64 v[212:213], v[122:123], 2, s[14:15]
	global_load_dwordx4 v[208:211], v[212:213], off
	s_ashr_i32 s13, s12, 31
	s_lshl_b64 s[20:21], s[12:13], 11
	v_lshl_add_u64 v[132:133], v[126:127], 0, s[20:21]
	v_mul_f32_e32 v64, v33, v33
	v_mul_f32_e32 v134, v39, v39
	v_mul_f32_e32 v135, v41, v41
	v_mul_f32_e32 v136, v43, v43
	v_fmac_f32_e32 v64, v32, v32
	v_fmac_f32_e32 v134, v38, v38
	v_mul_f32_e32 v137, v45, v45
	v_mul_f32_e32 v138, v47, v47
	v_fmac_f32_e32 v135, v40, v40
	v_fmac_f32_e32 v136, v42, v42
	v_fmac_f32_e32 v137, v44, v44
	v_fmac_f32_e32 v138, v46, v46
	s_waitcnt vmcnt(0)
	v_pk_add_f32 v[128:129], v[128:129], 1.0 op_sel_hi:[1,0]
	v_pk_add_f32 v[130:131], v[130:131], 1.0 op_sel_hi:[1,0]
	v_pk_mul_f32 v[128:129], v[0:1], v[128:129]
	v_pk_mul_f32 v[130:131], v[2:3], v[130:131]
	v_pk_mul_f32 v[128:129], v[32:33], v[128:129]
	v_pk_mul_f32 v[130:131], v[34:35], v[130:131]
	v_cvt_pk_bf16_f32 v128, v128, v129
	s_nop 0
	v_cvt_pk_bf16_f32 v129, v130, v131
	global_store_dwordx2 v[132:133], v[128:129], off
	v_pk_add_f32 v[200:201], v[200:201], 1.0 op_sel_hi:[1,0]
	v_pk_add_f32 v[202:203], v[202:203], 1.0 op_sel_hi:[1,0]
	v_pk_mul_f32 v[200:201], v[4:5], v[200:201]
	v_pk_mul_f32 v[202:203], v[6:7], v[202:203]
	v_pk_mul_f32 v[200:201], v[36:37], v[200:201]
	v_pk_mul_f32 v[202:203], v[38:39], v[202:203]
	v_cvt_pk_bf16_f32 v200, v200, v201
	s_nop 0
	v_cvt_pk_bf16_f32 v201, v202, v203
	global_store_dwordx2 v[132:133], v[200:201], off offset:512
	v_pk_add_f32 v[204:205], v[204:205], 1.0 op_sel_hi:[1,0]
	v_pk_add_f32 v[206:207], v[206:207], 1.0 op_sel_hi:[1,0]
	v_pk_mul_f32 v[204:205], v[8:9], v[204:205]
	v_pk_mul_f32 v[206:207], v[10:11], v[206:207]
	v_pk_mul_f32 v[204:205], v[40:41], v[204:205]
	v_pk_mul_f32 v[206:207], v[42:43], v[206:207]
	v_cvt_pk_bf16_f32 v204, v204, v205
	s_nop 0
	v_cvt_pk_bf16_f32 v205, v206, v207
	global_store_dwordx2 v[132:133], v[204:205], off offset:1024
	v_mul_f32_e32 v66, v35, v35
	v_mul_f32_e32 v67, v37, v37
	v_fmac_f32_e32 v66, v34, v34
	v_fmac_f32_e32 v67, v36, v36
	v_add_f32_e32 v64, v64, v66
	v_add_f32_e32 v66, v67, v134
	v_add_f32_e32 v67, v135, v136
	v_add_f32_e32 v64, v64, v66
	v_add_f32_e32 v134, v137, v138
	v_add_f32_e32 v64, v64, v67
	v_add_f32_e32 v64, v64, v134
	s_nop 1
	v_add_f32_dpp v64, v64, v64 quad_perm:[1,0,3,2] row_mask:0xf bank_mask:0xf
	s_nop 1
	v_add_f32_dpp v64, v64, v64 quad_perm:[2,3,0,1] row_mask:0xf bank_mask:0xf
	s_nop 1
	v_add_f32_dpp v64, v64, v64 row_half_mirror row_mask:0xf bank_mask:0xf
	s_nop 1
	v_add_f32_dpp v64, v64, v64 row_mirror row_mask:0xf bank_mask:0xf
	v_mov_b32_e32 v66, v64
	s_nop 1
	v_permlane16_swap_b32_e32 v64, v66
	v_add_f32_e32 v64, v64, v66
	v_mov_b32_e32 v66, v64
	s_nop 1
	v_permlane32_swap_b32_e32 v64, v66
	v_pk_add_f32 v[208:209], v[208:209], 1.0 op_sel_hi:[1,0]
	v_pk_add_f32 v[210:211], v[210:211], 1.0 op_sel_hi:[1,0]
	v_pk_mul_f32 v[208:209], v[12:13], v[208:209]
	v_pk_mul_f32 v[210:211], v[14:15], v[210:211]
	v_pk_mul_f32 v[208:209], v[44:45], v[208:209]
	v_pk_mul_f32 v[210:211], v[46:47], v[210:211]
	v_cvt_pk_bf16_f32 v208, v208, v209
	s_nop 0
	v_cvt_pk_bf16_f32 v209, v210, v211
	global_store_dwordx2 v[132:133], v[208:209], off offset:1536
	s_and_saveexec_b64 s[14:15], s[2:3]
	s_cbranch_execz .LBB0_258
	v_add_f32_e32 v64, v64, v66
	s_lshl_b64 s[12:13], s[12:13], 6
	v_cndmask_b32_e64 v64, 0, v64, s[4:5]
	v_lshl_add_u64 v[128:129], v[124:125], 0, s[12:13]
	v_mov_b32_e32 v66, v65
	v_mov_b32_e32 v67, v65
	global_store_dwordx4 v[128:129], v[64:67], off

.LBB0_265:
	s_min_i32 s7, s8, 0x8000
	s_ashr_i32 s7, s7, 11
	s_mul_hi_i32 s9, s7, 0x6000
	s_mulk_i32 s7, 0x6000
	s_add_u32 s7, s44, s7
	s_addc_u32 s9, s45, s9
	s_add_u32 s10, s7, 0x1000
	s_addc_u32 s11, s9, 0
	v_lshl_add_u64 v[66:67], v[116:117], 2, s[10:11]
	global_load_dwordx4 v[128:131], v[66:67], off
	v_lshl_add_u64 v[212:213], v[118:119], 2, s[10:11]
	global_load_dwordx4 v[200:203], v[212:213], off
	v_lshl_add_u64 v[212:213], v[120:121], 2, s[10:11]
	global_load_dwordx4 v[204:207], v[212:213], off
	v_lshl_add_u64 v[212:213], v[122:123], 2, s[10:11]
	global_load_dwordx4 v[208:211], v[212:213], off
	s_ashr_i32 s9, s8, 31
	s_lshl_b64 s[14:15], s[8:9], 11
	v_lshl_add_u64 v[132:133], v[126:127], 0, s[14:15]
	v_mul_f32_e32 v64, v101, v101
	v_mul_f32_e32 v134, v107, v107
	v_mul_f32_e32 v135, v109, v109
	v_mul_f32_e32 v136, v111, v111
	v_fmac_f32_e32 v64, v100, v100
	v_fmac_f32_e32 v134, v106, v106
	v_mul_f32_e32 v137, v113, v113
	v_mul_f32_e32 v138, v115, v115
	v_fmac_f32_e32 v135, v108, v108
	v_fmac_f32_e32 v136, v110, v110
	v_fmac_f32_e32 v137, v112, v112
	v_fmac_f32_e32 v138, v114, v114
	s_waitcnt vmcnt(0)
	v_pk_add_f32 v[128:129], v[128:129], 1.0 op_sel_hi:[1,0]
	v_pk_add_f32 v[130:131], v[130:131], 1.0 op_sel_hi:[1,0]
	v_pk_mul_f32 v[128:129], v[0:1], v[128:129]
	v_pk_mul_f32 v[130:131], v[2:3], v[130:131]
	v_pk_mul_f32 v[128:129], v[100:101], v[128:129]
	v_pk_mul_f32 v[130:131], v[102:103], v[130:131]
	v_cvt_pk_bf16_f32 v128, v128, v129
	s_nop 0
	v_cvt_pk_bf16_f32 v129, v130, v131
	global_store_dwordx2 v[132:133], v[128:129], off
	v_pk_add_f32 v[200:201], v[200:201], 1.0 op_sel_hi:[1,0]
	v_pk_add_f32 v[202:203], v[202:203], 1.0 op_sel_hi:[1,0]
	v_pk_mul_f32 v[200:201], v[4:5], v[200:201]
	v_pk_mul_f32 v[202:203], v[6:7], v[202:203]
	v_pk_mul_f32 v[200:201], v[104:105], v[200:201]
	v_pk_mul_f32 v[202:203], v[106:107], v[202:203]
	v_cvt_pk_bf16_f32 v200, v200, v201
	s_nop 0
	v_cvt_pk_bf16_f32 v201, v202, v203
	global_store_dwordx2 v[132:133], v[200:201], off offset:512
	v_pk_add_f32 v[204:205], v[204:205], 1.0 op_sel_hi:[1,0]
	v_pk_add_f32 v[206:207], v[206:207], 1.0 op_sel_hi:[1,0]
	v_pk_mul_f32 v[204:205], v[8:9], v[204:205]
	v_pk_mul_f32 v[206:207], v[10:11], v[206:207]
	v_pk_mul_f32 v[204:205], v[108:109], v[204:205]
	v_pk_mul_f32 v[206:207], v[110:111], v[206:207]
	v_cvt_pk_bf16_f32 v204, v204, v205
	s_nop 0
	v_cvt_pk_bf16_f32 v205, v206, v207
	global_store_dwordx2 v[132:133], v[204:205], off offset:1024
	v_mul_f32_e32 v66, v103, v103
	v_mul_f32_e32 v67, v105, v105
	v_fmac_f32_e32 v66, v102, v102
	v_fmac_f32_e32 v67, v104, v104
	v_add_f32_e32 v64, v64, v66
	v_add_f32_e32 v66, v67, v134
	v_add_f32_e32 v67, v135, v136
	v_add_f32_e32 v64, v64, v66
	v_add_f32_e32 v134, v137, v138
	v_add_f32_e32 v64, v64, v67
	v_add_f32_e32 v64, v64, v134
	s_nop 1
	v_add_f32_dpp v64, v64, v64 quad_perm:[1,0,3,2] row_mask:0xf bank_mask:0xf
	s_nop 1
	v_add_f32_dpp v64, v64, v64 quad_perm:[2,3,0,1] row_mask:0xf bank_mask:0xf
	s_nop 1
	v_add_f32_dpp v64, v64, v64 row_half_mirror row_mask:0xf bank_mask:0xf
	s_nop 1
	v_add_f32_dpp v64, v64, v64 row_mirror row_mask:0xf bank_mask:0xf
	v_mov_b32_e32 v66, v64
	s_nop 1
	v_permlane16_swap_b32_e32 v64, v66
	v_add_f32_e32 v64, v64, v66
	v_mov_b32_e32 v66, v64
	s_nop 1
	v_permlane32_swap_b32_e32 v64, v66
	v_pk_add_f32 v[208:209], v[208:209], 1.0 op_sel_hi:[1,0]
	v_pk_add_f32 v[210:211], v[210:211], 1.0 op_sel_hi:[1,0]
	v_pk_mul_f32 v[208:209], v[12:13], v[208:209]
	v_pk_mul_f32 v[210:211], v[14:15], v[210:211]
	v_pk_mul_f32 v[208:209], v[112:113], v[208:209]
	v_pk_mul_f32 v[210:211], v[114:115], v[210:211]
	v_cvt_pk_bf16_f32 v208, v208, v209
	s_nop 0
	v_cvt_pk_bf16_f32 v209, v210, v211
	global_store_dwordx2 v[132:133], v[208:209], off offset:1536
	s_and_saveexec_b64 s[10:11], s[2:3]
	s_cbranch_execz .LBB0_268
	v_add_f32_e32 v64, v64, v66
	s_lshl_b64 s[8:9], s[8:9], 6
	v_cndmask_b32_e64 v64, 0, v64, s[4:5]
	v_lshl_add_u64 v[128:129], v[124:125], 0, s[8:9]
	v_mov_b32_e32 v66, v65
	v_mov_b32_e32 v67, v65
	global_store_dwordx4 v[128:129], v[64:67], off
	s_or_b64 exec, exec, s[10:11]
	s_add_i32 s8, s0, s6
	s_cmp_gt_i32 s8, 0x8fff
	s_cbranch_scc0 .LBB0_269

.LBB0_269:
	s_min_i32 s7, s8, 0x8000
	s_ashr_i32 s7, s7, 11
	s_mul_hi_i32 s9, s7, 0x6000
	s_mulk_i32 s7, 0x6000
	s_add_u32 s7, s44, s7
	s_addc_u32 s9, s45, s9
	s_add_u32 s10, s7, 0x1000
	s_addc_u32 s11, s9, 0
	v_lshl_add_u64 v[66:67], v[116:117], 2, s[10:11]
	global_load_dwordx4 v[128:131], v[66:67], off
	v_lshl_add_u64 v[212:213], v[118:119], 2, s[10:11]
	global_load_dwordx4 v[200:203], v[212:213], off
	v_lshl_add_u64 v[212:213], v[120:121], 2, s[10:11]
	global_load_dwordx4 v[204:207], v[212:213], off
	v_lshl_add_u64 v[212:213], v[122:123], 2, s[10:11]
	global_load_dwordx4 v[208:211], v[212:213], off
	s_ashr_i32 s9, s8, 31
	s_lshl_b64 s[14:15], s[8:9], 11
	v_lshl_add_u64 v[132:133], v[126:127], 0, s[14:15]
	v_mul_f32_e32 v64, v97, v97
	v_mul_f32_e32 v134, v95, v95
	v_mul_f32_e32 v135, v89, v89
	v_mul_f32_e32 v136, v91, v91
	v_fmac_f32_e32 v64, v96, v96
	v_fmac_f32_e32 v134, v94, v94
	v_mul_f32_e32 v137, v85, v85
	v_mul_f32_e32 v138, v87, v87
	v_fmac_f32_e32 v135, v88, v88
	v_fmac_f32_e32 v136, v90, v90
	v_fmac_f32_e32 v137, v84, v84
	v_fmac_f32_e32 v138, v86, v86
	s_waitcnt vmcnt(0)
	v_pk_add_f32 v[128:129], v[128:129], 1.0 op_sel_hi:[1,0]
	v_pk_add_f32 v[130:131], v[130:131], 1.0 op_sel_hi:[1,0]
	v_pk_mul_f32 v[128:129], v[0:1], v[128:129]
	v_pk_mul_f32 v[130:131], v[2:3], v[130:131]
	v_pk_mul_f32 v[128:129], v[96:97], v[128:129]
	v_pk_mul_f32 v[130:131], v[98:99], v[130:131]
	v_cvt_pk_bf16_f32 v128, v128, v129
	s_nop 0
	v_cvt_pk_bf16_f32 v129, v130, v131
	global_store_dwordx2 v[132:133], v[128:129], off
	v_pk_add_f32 v[200:201], v[200:201], 1.0 op_sel_hi:[1,0]
	v_pk_add_f32 v[202:203], v[202:203], 1.0 op_sel_hi:[1,0]
	v_pk_mul_f32 v[200:201], v[4:5], v[200:201]
	v_pk_mul_f32 v[202:203], v[6:7], v[202:203]
	v_pk_mul_f32 v[200:201], v[92:93], v[200:201]
	v_pk_mul_f32 v[202:203], v[94:95], v[202:203]
	v_cvt_pk_bf16_f32 v200, v200, v201
	s_nop 0
	v_cvt_pk_bf16_f32 v201, v202, v203
	global_store_dwordx2 v[132:133], v[200:201], off offset:512
	v_pk_add_f32 v[204:205], v[204:205], 1.0 op_sel_hi:[1,0]
	v_pk_add_f32 v[206:207], v[206:207], 1.0 op_sel_hi:[1,0]
	v_pk_mul_f32 v[204:205], v[8:9], v[204:205]
	v_pk_mul_f32 v[206:207], v[10:11], v[206:207]
	v_pk_mul_f32 v[204:205], v[88:89], v[204:205]
	v_pk_mul_f32 v[206:207], v[90:91], v[206:207]
	v_cvt_pk_bf16_f32 v204, v204, v205
	s_nop 0
	v_cvt_pk_bf16_f32 v205, v206, v207
	global_store_dwordx2 v[132:133], v[204:205], off offset:1024
	v_mul_f32_e32 v66, v99, v99
	v_mul_f32_e32 v67, v93, v93
	v_fmac_f32_e32 v66, v98, v98
	v_fmac_f32_e32 v67, v92, v92
	v_add_f32_e32 v64, v64, v66
	v_add_f32_e32 v66, v67, v134
	v_add_f32_e32 v67, v135, v136
	v_add_f32_e32 v64, v64, v66
	v_add_f32_e32 v134, v137, v138
	v_add_f32_e32 v64, v64, v67
	v_add_f32_e32 v64, v64, v134
	s_nop 1
	v_add_f32_dpp v64, v64, v64 quad_perm:[1,0,3,2] row_mask:0xf bank_mask:0xf
	s_nop 1
	v_add_f32_dpp v64, v64, v64 quad_perm:[2,3,0,1] row_mask:0xf bank_mask:0xf
	s_nop 1
	v_add_f32_dpp v64, v64, v64 row_half_mirror row_mask:0xf bank_mask:0xf
	s_nop 1
	v_add_f32_dpp v64, v64, v64 row_mirror row_mask:0xf bank_mask:0xf
	v_mov_b32_e32 v66, v64
	s_nop 1
	v_permlane16_swap_b32_e32 v64, v66
	v_add_f32_e32 v64, v64, v66
	v_mov_b32_e32 v66, v64
	s_nop 1
	v_permlane32_swap_b32_e32 v64, v66
	v_pk_add_f32 v[208:209], v[208:209], 1.0 op_sel_hi:[1,0]
	v_pk_add_f32 v[210:211], v[210:211], 1.0 op_sel_hi:[1,0]
	v_pk_mul_f32 v[208:209], v[12:13], v[208:209]
	v_pk_mul_f32 v[210:211], v[14:15], v[210:211]
	v_pk_mul_f32 v[208:209], v[84:85], v[208:209]
	v_pk_mul_f32 v[210:211], v[86:87], v[210:211]
	v_cvt_pk_bf16_f32 v208, v208, v209
	s_nop 0
	v_cvt_pk_bf16_f32 v209, v210, v211
	global_store_dwordx2 v[132:133], v[208:209], off offset:1536
	s_and_saveexec_b64 s[10:11], s[2:3]
	s_cbranch_execz .LBB0_271
	v_add_f32_e32 v64, v64, v66
	s_lshl_b64 s[8:9], s[8:9], 6
	v_cndmask_b32_e64 v64, 0, v64, s[4:5]
	v_lshl_add_u64 v[128:129], v[124:125], 0, s[8:9]
	v_mov_b32_e32 v66, v65
	v_mov_b32_e32 v67, v65
	global_store_dwordx4 v[128:129], v[64:67], off

.LBB0_272:
	s_min_i32 s7, s6, 0x8000
	s_ashr_i32 s7, s7, 11
	s_mul_hi_i32 s8, s7, 0x6000
	s_mulk_i32 s7, 0x6000
	s_add_u32 s7, s44, s7
	s_addc_u32 s9, s45, s8
	s_add_u32 s8, s7, 0x1000
	s_addc_u32 s9, s9, 0
	v_lshl_add_u64 v[66:67], v[116:117], 2, s[8:9]
	global_load_dwordx4 v[128:131], v[66:67], off
	v_lshl_add_u64 v[212:213], v[118:119], 2, s[8:9]
	global_load_dwordx4 v[200:203], v[212:213], off
	v_lshl_add_u64 v[212:213], v[120:121], 2, s[8:9]
	global_load_dwordx4 v[204:207], v[212:213], off
	v_lshl_add_u64 v[212:213], v[122:123], 2, s[8:9]
	global_load_dwordx4 v[208:211], v[212:213], off
	s_ashr_i32 s7, s6, 31
	s_lshl_b64 s[10:11], s[6:7], 11
	v_lshl_add_u64 v[132:133], v[126:127], 0, s[10:11]
	v_mul_f32_e32 v64, v81, v81
	v_mul_f32_e32 v134, v79, v79
	v_mul_f32_e32 v135, v73, v73
	v_mul_f32_e32 v136, v75, v75
	v_fmac_f32_e32 v64, v80, v80
	v_fmac_f32_e32 v134, v78, v78
	v_mul_f32_e32 v137, v69, v69
	v_mul_f32_e32 v138, v71, v71
	v_fmac_f32_e32 v135, v72, v72
	v_fmac_f32_e32 v136, v74, v74
	v_fmac_f32_e32 v137, v68, v68
	v_fmac_f32_e32 v138, v70, v70
	s_waitcnt vmcnt(0)
	v_pk_add_f32 v[128:129], v[128:129], 1.0 op_sel_hi:[1,0]
	v_pk_add_f32 v[130:131], v[130:131], 1.0 op_sel_hi:[1,0]
	v_pk_mul_f32 v[128:129], v[0:1], v[128:129]
	v_pk_mul_f32 v[130:131], v[2:3], v[130:131]
	v_pk_mul_f32 v[128:129], v[80:81], v[128:129]
	v_pk_mul_f32 v[130:131], v[82:83], v[130:131]
	v_cvt_pk_bf16_f32 v128, v128, v129
	s_nop 0
	v_cvt_pk_bf16_f32 v129, v130, v131
	global_store_dwordx2 v[132:133], v[128:129], off
	v_pk_add_f32 v[200:201], v[200:201], 1.0 op_sel_hi:[1,0]
	v_pk_add_f32 v[202:203], v[202:203], 1.0 op_sel_hi:[1,0]
	v_pk_mul_f32 v[200:201], v[4:5], v[200:201]
	v_pk_mul_f32 v[202:203], v[6:7], v[202:203]
	v_pk_mul_f32 v[200:201], v[76:77], v[200:201]
	v_pk_mul_f32 v[202:203], v[78:79], v[202:203]
	v_cvt_pk_bf16_f32 v200, v200, v201
	s_nop 0
	v_cvt_pk_bf16_f32 v201, v202, v203
	global_store_dwordx2 v[132:133], v[200:201], off offset:512
	v_pk_add_f32 v[204:205], v[204:205], 1.0 op_sel_hi:[1,0]
	v_pk_add_f32 v[206:207], v[206:207], 1.0 op_sel_hi:[1,0]
	v_pk_mul_f32 v[204:205], v[8:9], v[204:205]
	v_pk_mul_f32 v[206:207], v[10:11], v[206:207]
	v_pk_mul_f32 v[204:205], v[72:73], v[204:205]
	v_pk_mul_f32 v[206:207], v[74:75], v[206:207]
	v_cvt_pk_bf16_f32 v204, v204, v205
	s_nop 0
	v_cvt_pk_bf16_f32 v205, v206, v207
	global_store_dwordx2 v[132:133], v[204:205], off offset:1024
	v_mul_f32_e32 v66, v83, v83
	v_mul_f32_e32 v67, v77, v77
	v_fmac_f32_e32 v66, v82, v82
	v_fmac_f32_e32 v67, v76, v76
	v_add_f32_e32 v64, v64, v66
	v_add_f32_e32 v66, v67, v134
	v_add_f32_e32 v67, v135, v136
	v_add_f32_e32 v64, v64, v66
	v_add_f32_e32 v134, v137, v138
	v_add_f32_e32 v64, v64, v67
	v_add_f32_e32 v64, v64, v134
	s_nop 1
	v_add_f32_dpp v64, v64, v64 quad_perm:[1,0,3,2] row_mask:0xf bank_mask:0xf
	s_nop 1
	v_add_f32_dpp v64, v64, v64 quad_perm:[2,3,0,1] row_mask:0xf bank_mask:0xf
	s_nop 1
	v_add_f32_dpp v64, v64, v64 row_half_mirror row_mask:0xf bank_mask:0xf
	s_nop 1
	v_add_f32_dpp v64, v64, v64 row_mirror row_mask:0xf bank_mask:0xf
	v_mov_b32_e32 v66, v64
	s_nop 1
	v_permlane16_swap_b32_e32 v64, v66
	v_add_f32_e32 v64, v64, v66
	v_mov_b32_e32 v66, v64
	s_nop 1
	v_permlane32_swap_b32_e32 v64, v66
	v_pk_add_f32 v[208:209], v[208:209], 1.0 op_sel_hi:[1,0]
	v_pk_add_f32 v[210:211], v[210:211], 1.0 op_sel_hi:[1,0]
	v_pk_mul_f32 v[208:209], v[12:13], v[208:209]
	v_pk_mul_f32 v[210:211], v[14:15], v[210:211]
	v_pk_mul_f32 v[208:209], v[68:69], v[208:209]
	v_pk_mul_f32 v[210:211], v[70:71], v[210:211]
	v_cvt_pk_bf16_f32 v208, v208, v209
	s_nop 0
	v_cvt_pk_bf16_f32 v209, v210, v211
	global_store_dwordx2 v[132:133], v[208:209], off offset:1536
	s_and_saveexec_b64 s[8:9], s[2:3]
	s_cbranch_execz .LBB0_242
	v_add_f32_e32 v64, v64, v66
	s_lshl_b64 s[6:7], s[6:7], 6
	v_cndmask_b32_e64 v64, 0, v64, s[4:5]
	v_lshl_add_u64 v[128:129], v[124:125], 0, s[6:7]
	v_mov_b32_e32 v66, v65
	v_mov_b32_e32 v67, v65
	global_store_dwordx4 v[128:129], v[64:67], off
	s_branch .LBB0_242
